# v27 + first k-iteration of EpiResid GEMMs waits vmcnt(8) so the y prefetch stays in flight
# baseline (speedup 1.0000x reference)
.LBB0_680:
	s_waitcnt vmcnt(0)
	ds_write_b32 v2, v246
	v_ashrrev_i32_e32 v103, 6, v100
	v_lshrrev_b32_e32 v0, 30, v103
	v_add_u32_e32 v0, v103, v0
	v_ashrrev_i32_e32 v10, 2, v0
	v_mul_i32_i24_e32 v0, 4, v10
	v_ashrrev_i32_e32 v6, 3, v100
	v_sub_u32_e32 v11, v103, v0
	v_lshrrev_b32_e32 v13, 4, v100
	v_add_u32_e32 v0, s4, v6
	v_xor_b32_e32 v7, v13, v100
	v_ashrrev_i32_e32 v1, 31, v0
	v_lshlrev_b64 v[0:1], 11, v[0:1]
	v_lshlrev_b32_e32 v7, 4, v7
	v_lshlrev_b32_e32 v109, 4, v100
	s_and_b32 s8, s2, 0xffffff00
	v_lshl_add_u64 v[4:5], s[50:51], 0, v[0:1]
	v_and_b32_e32 v128, 0x70, v7
	v_readfirstlane_b32 s2, v109
	v_add_u32_e32 v14, 0x2000, v109
	v_lshl_add_u64 v[4:5], v[4:5], 0, v[128:129]
	s_mov_b32 m0, s2
	s_mov_b64 s[10:11], 0x20000
	v_readfirstlane_b32 s2, v14
	ds_write_b32 v2, v3 offset:2048
	v_lshl_add_u64 v[2:3], v[4:5], 0, s[10:11]
	s_mov_b32 m0, s2
	s_mov_b64 s[12:13], 0x40000
	v_lshl_add_u64 v[2:3], v[4:5], 0, s[12:13]
	v_add_u32_e32 v4, 0x4000, v109
	v_add_u32_e32 v6, s8, v6
	v_readfirstlane_b32 s2, v4
	v_ashrrev_i32_e32 v7, 31, v6
	s_mov_b32 m0, s2
	v_lshlrev_b64 v[6:7], 11, v[6:7]
	v_add_u32_e32 v2, 0x6000, v109
	v_lshl_add_u64 v[8:9], s[60:61], 0, v[6:7]
	v_readfirstlane_b32 s2, v2
	v_add_u32_e32 v4, 0x8000, v109
	v_lshl_add_u64 v[8:9], v[8:9], 0, v[128:129]
	s_mov_b32 m0, s2
	v_readfirstlane_b32 s2, v4
	v_add_u32_e32 v4, 0xa000, v109
	v_lshl_add_u64 v[2:3], v[8:9], 0, s[10:11]
	s_mov_b32 m0, s2
	v_readfirstlane_b32 s2, v4
	v_lshl_add_u64 v[2:3], v[8:9], 0, s[12:13]
	s_mov_b32 m0, s2
	s_mov_b64 s[2:3], 0x60000
	v_add_u32_e32 v4, 0xc000, v109
	v_lshl_add_u64 v[2:3], v[8:9], 0, s[2:3]
	v_readfirstlane_b32 s2, v4
	s_mov_b32 m0, s2
	v_and_b32_e32 v102, 31, v100
	v_lshlrev_b32_e32 v105, 6, v11
	v_or_b32_e32 v3, v105, v102
	v_mul_i32_i24_e32 v106, 0x60, v10
	v_bfe_u32 v12, v100, 5, 1
	v_lshrrev_b32_e32 v104, 1, v100
	v_lshlrev_b32_e32 v112, 7, v3
	v_or_b32_e32 v3, v106, v102
	v_bfe_u32 v2, v100, 1, 3
	v_lshlrev_b32_e32 v113, 7, v3
	v_bitop3_b32 v3, v12, v104, 7 bitop3:0x78
	v_lshlrev_b32_e32 v111, 4, v3
	v_bitop3_b32 v3, v12, v2, 2 bitop3:0x36
	v_lshlrev_b32_e32 v110, 4, v3
	v_bitop3_b32 v3, v12, v2, 4 bitop3:0x36
	v_bitop3_b32 v2, v12, v2, 6 bitop3:0x36
	v_lshlrev_b32_e32 v107, 4, v2
	v_bitop3_b32 v2, v13, 7, v100 bitop3:0x48
	v_lshlrev_b32_e32 v2, 4, v2
	v_or_b32_e32 v6, v6, v2
	v_or_b32_e32 v0, v0, v2
	v_and_b32_e32 v101, 63, v100
	v_lshlrev_b32_e32 v108, 4, v3
	v_add_u32_e32 v114, 0x6000, v112
	v_lshl_add_u64 v[96:97], s[62:63], 0, v[6:7]
	v_lshl_add_u64 v[98:99], s[14:15], 0, v[0:1]
	s_mov_b32 s7, 0
	s_mov_b64 s[2:3], 0
	v_mov_b32_e32 v33, v32
	v_mov_b32_e32 v34, v32
	v_mov_b32_e32 v35, v32
	v_mov_b32_e32 v36, v32
	v_mov_b32_e32 v37, v32
	v_mov_b32_e32 v38, v32
	v_mov_b32_e32 v39, v32
	v_mov_b32_e32 v40, v32
	v_mov_b32_e32 v41, v32
	v_mov_b32_e32 v42, v32
	v_mov_b32_e32 v43, v32
	v_mov_b32_e32 v44, v32
	v_mov_b32_e32 v45, v32
	v_mov_b32_e32 v46, v32
	v_mov_b32_e32 v47, v32
	v_mov_b32_e32 v64, v32
	v_mov_b32_e32 v65, v32
	v_mov_b32_e32 v66, v32
	v_mov_b32_e32 v67, v32
	v_mov_b32_e32 v68, v32
	v_mov_b32_e32 v69, v32
	v_mov_b32_e32 v70, v32
	v_mov_b32_e32 v71, v32
	v_mov_b32_e32 v72, v32
	v_mov_b32_e32 v73, v32
	v_mov_b32_e32 v74, v32
	v_mov_b32_e32 v75, v32
	v_mov_b32_e32 v76, v32
	v_mov_b32_e32 v77, v32
	v_mov_b32_e32 v78, v32
	v_mov_b32_e32 v79, v32
	v_mov_b32_e32 v0, v32
	v_mov_b32_e32 v1, v32
	v_mov_b32_e32 v2, v32
	v_mov_b32_e32 v3, v32
	v_mov_b32_e32 v4, v32
	v_mov_b32_e32 v5, v32
	v_mov_b32_e32 v6, v32
	v_mov_b32_e32 v7, v32
	v_mov_b32_e32 v8, v32
	v_mov_b32_e32 v9, v32
	v_mov_b32_e32 v10, v32
	v_mov_b32_e32 v11, v32
	v_mov_b32_e32 v12, v32
	v_mov_b32_e32 v13, v32
	v_mov_b32_e32 v14, v32
	v_mov_b32_e32 v15, v32
	v_mov_b32_e32 v80, v32
	v_mov_b32_e32 v81, v32
	v_mov_b32_e32 v82, v32
	v_mov_b32_e32 v83, v32
	v_mov_b32_e32 v84, v32
	v_mov_b32_e32 v85, v32
	v_mov_b32_e32 v86, v32
	v_mov_b32_e32 v87, v32
	v_mov_b32_e32 v88, v32
	v_mov_b32_e32 v89, v32
	v_mov_b32_e32 v90, v32
	v_mov_b32_e32 v91, v32
	v_mov_b32_e32 v92, v32
	v_mov_b32_e32 v93, v32
	v_mov_b32_e32 v94, v32
	v_mov_b32_e32 v95, v32
	v_mov_b32_e32 v48, v32
	v_mov_b32_e32 v49, v32
	v_mov_b32_e32 v50, v32
	v_mov_b32_e32 v51, v32
	v_mov_b32_e32 v52, v32
	v_mov_b32_e32 v53, v32
	v_mov_b32_e32 v54, v32
	v_mov_b32_e32 v55, v32
	v_mov_b32_e32 v56, v32
	v_mov_b32_e32 v57, v32
	v_mov_b32_e32 v58, v32
	v_mov_b32_e32 v59, v32
	v_mov_b32_e32 v60, v32
	v_mov_b32_e32 v61, v32
	v_mov_b32_e32 v62, v32
	v_mov_b32_e32 v63, v32
	v_mov_b32_e32 v16, v32
	v_mov_b32_e32 v17, v32
	v_mov_b32_e32 v18, v32
	v_mov_b32_e32 v19, v32
	v_mov_b32_e32 v20, v32
	v_mov_b32_e32 v21, v32
	v_mov_b32_e32 v22, v32
	v_mov_b32_e32 v23, v32
	v_mov_b32_e32 v24, v32
	v_mov_b32_e32 v25, v32
	v_mov_b32_e32 v26, v32
	v_mov_b32_e32 v27, v32
	v_mov_b32_e32 v28, v32
	v_mov_b32_e32 v29, v32
	v_mov_b32_e32 v30, v32
	v_mov_b32_e32 v31, v32
	s_mov_b64 s[12:13], 0x8794080
	s_mov_b64 s[16:17], 0x87b4080
	s_mov_b64 s[18:19], 0x87d4080
	v_add_u32_e32 v243, s4, v106
	v_lshrrev_b32_e32 v244, 4, v101
	v_or_b32_e32 v243, v243, v244
	v_and_b32_e32 v244, 15, v100
	v_add_u32_e32 v245, s8, v105
	v_lshl_or_b32 v244, v244, 2, v245
	v_lshlrev_b32_e32 v243, 12, v243
	v_lshl_add_u32 v243, v244, 2, v243
	global_load_dwordx4 v[198:201], v243, s[40:41]
	v_add_u32_e32 v243, 0x4000, v243
	global_load_dwordx4 v[202:205], v243, s[40:41]
	v_add_u32_e32 v243, 0x4000, v243
	global_load_dwordx4 v[206:209], v243, s[40:41]
	v_add_u32_e32 v243, 0x4000, v243
	global_load_dwordx4 v[210:213], v243, s[40:41]
	v_add_u32_e32 v243, 0x4000, v243
	global_load_dwordx4 v[214:217], v243, s[40:41]
	v_add_u32_e32 v243, 0x4000, v243
	global_load_dwordx4 v[218:221], v243, s[40:41]
	v_add_u32_e32 v243, 0x4000, v243
	global_load_dwordx4 v[222:225], v243, s[40:41]
	v_add_u32_e32 v243, 0x4000, v243
	global_load_dwordx4 v[226:229], v243, s[40:41]
	s_add_i32 s9, s7, 1
	s_bitcmp1_b32 s9, 0
	s_cselect_b32 s10, 0xe000, 0
	v_add_u32_e32 v115, s10, v109
	v_lshl_add_u64 v[116:117], v[98:99], 0, s[2:3]
	v_readfirstlane_b32 s10, v115
	v_add_u32_e32 v120, 0x2000, v115
	v_lshl_add_u64 v[118:119], v[116:117], 0, s[12:13]
	s_mov_b32 m0, s10
	v_readfirstlane_b32 s10, v120
	s_waitcnt vmcnt(8)
	s_waitcnt vmcnt(8) lgkmcnt(0)
	s_barrier
	s_branch .Lbody_LBB0681

.Lbody_LBB0681:
	global_load_lds_dwordx4 v[118:119], off
	v_lshl_add_u64 v[118:119], v[116:117], 0, s[16:17]
	s_mov_b32 m0, s10
	v_lshl_add_u64 v[116:117], v[116:117], 0, s[18:19]
	global_load_lds_dwordx4 v[118:119], off
	v_add_u32_e32 v118, 0x4000, v115
	v_add_u32_e32 v120, 0x6000, v115
	v_readfirstlane_b32 s10, v118
	s_mov_b32 m0, s10
	s_mov_b64 s[10:11], 0x6a94080
	global_load_lds_dwordx4 v[116:117], off
	v_lshl_add_u64 v[116:117], v[96:97], 0, s[2:3]
	v_lshl_add_u64 v[118:119], v[116:117], 0, s[10:11]
	v_readfirstlane_b32 s10, v120
	s_mov_b32 m0, s10
	s_mov_b64 s[10:11], 0x6ab4080
	v_add_u32_e32 v120, 0x8000, v115
	global_load_lds_dwordx4 v[118:119], off
	v_lshl_add_u64 v[118:119], v[116:117], 0, s[10:11]
	v_readfirstlane_b32 s10, v120
	s_mov_b32 m0, s10
	s_mov_b64 s[10:11], 0x6ad4080
	v_add_u32_e32 v120, 0xa000, v115
	global_load_lds_dwordx4 v[118:119], off
	v_lshl_add_u64 v[118:119], v[116:117], 0, s[10:11]
	v_readfirstlane_b32 s10, v120
	s_mov_b32 m0, s10
	s_mov_b64 s[10:11], 0x6af4080
	v_add_u32_e32 v115, 0xc000, v115
	v_lshl_add_u64 v[116:117], v[116:117], 0, s[10:11]
	v_readfirstlane_b32 s10, v115
	global_load_lds_dwordx4 v[118:119], off
	s_mov_b32 m0, s10
	s_nop 0
	global_load_lds_dwordx4 v[116:117], off
	s_bitcmp1_b32 s7, 0
	s_cselect_b32 s7, 0xe000, 0
	v_add_u32_e32 v115, s7, v114
	v_add_u32_e32 v120, v115, v111
	ds_read_b128 v[116:119], v120 offset:0
	v_add_u32_e32 v128, s7, v113
	ds_read_b128 v[120:123], v120 offset:0x1000
	v_add_u32_e32 v134, v128, v111
	ds_read_b128 v[124:127], v134 offset:0
	ds_read_b128 v[130:133], v134 offset:0x1000
	ds_read_b128 v[134:137], v134 offset:0x2000
	v_add_u32_e32 v148, v115, v110
	ds_read_b128 v[144:147], v148 offset:0
	ds_read_b128 v[148:151], v148 offset:0x1000
	v_add_u32_e32 v152, v128, v110
	ds_read_b128 v[182:185], v152 offset:0
	ds_read_b128 v[186:189], v152 offset:0x1000
	ds_read_b128 v[190:193], v152 offset:0x2000
	s_waitcnt lgkmcnt(5)
	s_nop 0
	v_mfma_f32_32x32x16_bf16 v[64:79], v[116:119], v[124:127], v[64:79]
	v_mfma_f32_32x32x16_bf16 v[32:47], v[116:119], v[130:133], v[32:47]
	v_mfma_f32_32x32x16_bf16 v[0:15], v[116:119], v[134:137], v[0:15]
	v_mfma_f32_32x32x16_bf16 v[80:95], v[120:123], v[124:127], v[80:95]
	v_mfma_f32_32x32x16_bf16 v[48:63], v[120:123], v[130:133], v[48:63]
	v_mfma_f32_32x32x16_bf16 v[16:31], v[120:123], v[134:137], v[16:31]
	v_add_u32_e32 v120, v115, v108
	ds_read_b128 v[116:119], v120 offset:0
	ds_read_b128 v[120:123], v120 offset:0x1000
	v_add_u32_e32 v134, v128, v108
	ds_read_b128 v[124:127], v134 offset:0
	ds_read_b128 v[130:133], v134 offset:0x1000
	ds_read_b128 v[134:137], v134 offset:0x2000
	s_waitcnt lgkmcnt(5)
	s_nop 0
	v_mfma_f32_32x32x16_bf16 v[64:79], v[144:147], v[182:185], v[64:79]
	v_mfma_f32_32x32x16_bf16 v[32:47], v[144:147], v[186:189], v[32:47]
	v_mfma_f32_32x32x16_bf16 v[0:15], v[144:147], v[190:193], v[0:15]
	v_mfma_f32_32x32x16_bf16 v[80:95], v[148:151], v[182:185], v[80:95]
	v_mfma_f32_32x32x16_bf16 v[48:63], v[148:151], v[186:189], v[48:63]
	v_mfma_f32_32x32x16_bf16 v[16:31], v[148:151], v[190:193], v[16:31]
	v_add_u32_e32 v115, v115, v107
	ds_read_b128 v[144:147], v115 offset:0
	ds_read_b128 v[148:151], v115 offset:0x1000
	v_add_u32_e32 v115, v128, v107
	ds_read_b128 v[182:185], v115 offset:0
	ds_read_b128 v[186:189], v115 offset:0x1000
	ds_read_b128 v[190:193], v115 offset:0x2000
	s_waitcnt lgkmcnt(5)
	s_nop 0
	v_mfma_f32_32x32x16_bf16 v[64:79], v[116:119], v[124:127], v[64:79]
	v_mfma_f32_32x32x16_bf16 v[32:47], v[116:119], v[130:133], v[32:47]
	v_mfma_f32_32x32x16_bf16 v[0:15], v[116:119], v[134:137], v[0:15]
	v_mfma_f32_32x32x16_bf16 v[80:95], v[120:123], v[124:127], v[80:95]
	v_mfma_f32_32x32x16_bf16 v[48:63], v[120:123], v[130:133], v[48:63]
	v_mfma_f32_32x32x16_bf16 v[16:31], v[120:123], v[134:137], v[16:31]
	s_waitcnt lgkmcnt(0)
	s_nop 0
	v_mfma_f32_32x32x16_bf16 v[64:79], v[144:147], v[182:185], v[64:79]
	v_mfma_f32_32x32x16_bf16 v[32:47], v[144:147], v[186:189], v[32:47]
	v_mfma_f32_32x32x16_bf16 v[0:15], v[144:147], v[190:193], v[0:15]
	v_mfma_f32_32x32x16_bf16 v[80:95], v[148:151], v[182:185], v[80:95]
	v_mfma_f32_32x32x16_bf16 v[48:63], v[148:151], v[186:189], v[48:63]
	v_mfma_f32_32x32x16_bf16 v[16:31], v[148:151], v[190:193], v[16:31]
	s_add_u32 s2, s2, 0x80
	s_addc_u32 s3, s3, 0
	s_cmpk_eq_i32 s2, 0x780
	s_mov_b32 s7, s9
	s_cbranch_scc0 .LBB0_681
	s_waitcnt vmcnt(0)
	s_waitcnt vmcnt(0) lgkmcnt(0)
	s_barrier
	v_add_u32_e32 v109, 0x14000, v112
	v_add_u32_e32 v112, v109, v111
	ds_read_b128 v[96:99], v112 offset:0
	v_add_u32_e32 v128, 0xe000, v113
	ds_read_b128 v[112:115], v112 offset:0x1000
	v_add_u32_e32 v111, v128, v111
	ds_read_b128 v[116:119], v111 offset:0
	ds_read_b128 v[120:123], v111 offset:0x1000
	ds_read_b128 v[124:127], v111 offset:0x2000
	v_add_u32_e32 v111, v109, v110
	ds_read_b128 v[130:133], v111 offset:0
	ds_read_b128 v[134:137], v111 offset:0x1000
	v_add_u32_e32 v110, v128, v110
	ds_read_b128 v[144:147], v110 offset:0
	ds_read_b128 v[148:151], v110 offset:0x1000
	ds_read_b128 v[182:185], v110 offset:0x2000
	s_waitcnt lgkmcnt(5)
	s_nop 0
	v_mfma_f32_32x32x16_bf16 v[64:79], v[96:99], v[116:119], v[64:79]
	v_mfma_f32_32x32x16_bf16 v[32:47], v[96:99], v[120:123], v[32:47]
	v_mfma_f32_32x32x16_bf16 v[0:15], v[96:99], v[124:127], v[0:15]
	v_mfma_f32_32x32x16_bf16 v[48:63], v[112:115], v[120:123], v[48:63]
	v_mfma_f32_32x32x16_bf16 v[16:31], v[112:115], v[124:127], v[16:31]
	v_mfma_f32_32x32x16_bf16 v[80:95], v[112:115], v[116:119], v[80:95]
	v_add_u32_e32 v110, v109, v108
	ds_read_b128 v[96:99], v110 offset:0
	ds_read_b128 v[110:113], v110 offset:0x1000
	v_add_u32_e32 v108, v128, v108
	ds_read_b128 v[114:117], v108 offset:0
	ds_read_b128 v[118:121], v108 offset:0x1000
	ds_read_b128 v[122:125], v108 offset:0x2000
	s_waitcnt lgkmcnt(5)
	s_nop 0
	v_mfma_f32_32x32x16_bf16 v[64:79], v[130:133], v[144:147], v[64:79]
	v_mfma_f32_32x32x16_bf16 v[32:47], v[130:133], v[148:151], v[32:47]
	v_mfma_f32_32x32x16_bf16 v[0:15], v[130:133], v[182:185], v[0:15]
	v_mfma_f32_32x32x16_bf16 v[48:63], v[134:137], v[148:151], v[48:63]
	v_mfma_f32_32x32x16_bf16 v[16:31], v[134:137], v[182:185], v[16:31]
	v_mfma_f32_32x32x16_bf16 v[80:95], v[134:137], v[144:147], v[80:95]
	v_add_u32_e32 v108, v109, v107
	ds_read_b128 v[130:133], v108 offset:0
	ds_read_b128 v[134:137], v108 offset:0x1000
	v_add_u32_e32 v107, v128, v107
	ds_read_b128 v[144:147], v107 offset:0
	ds_read_b128 v[148:151], v107 offset:0x1000
	ds_read_b128 v[182:185], v107 offset:0x2000
	s_waitcnt lgkmcnt(5)
	s_nop 0
	v_mfma_f32_32x32x16_bf16 v[64:79], v[96:99], v[114:117], v[64:79]
	v_mfma_f32_32x32x16_bf16 v[32:47], v[96:99], v[118:121], v[32:47]
	v_mfma_f32_32x32x16_bf16 v[0:15], v[96:99], v[122:125], v[0:15]
	v_mfma_f32_32x32x16_bf16 v[48:63], v[110:113], v[118:121], v[48:63]
	v_mfma_f32_32x32x16_bf16 v[16:31], v[110:113], v[122:125], v[16:31]
	v_mfma_f32_32x32x16_bf16 v[80:95], v[110:113], v[114:117], v[80:95]
	s_waitcnt lgkmcnt(0)
	s_nop 0
	v_mfma_f32_32x32x16_bf16 v[64:79], v[130:133], v[144:147], v[64:79]
	v_mfma_f32_32x32x16_bf16 v[32:47], v[130:133], v[148:151], v[32:47]
	v_mfma_f32_32x32x16_bf16 v[0:15], v[130:133], v[182:185], v[0:15]
	v_mfma_f32_32x32x16_bf16 v[48:63], v[134:137], v[148:151], v[48:63]
	v_mfma_f32_32x32x16_bf16 v[16:31], v[134:137], v[182:185], v[16:31]
	v_mfma_f32_32x32x16_bf16 v[80:95], v[134:137], v[144:147], v[80:95]
	v_add_u32_e32 v96, s4, v106
	v_lshrrev_b32_e32 v128, 4, v101
	v_and_b32_e32 v112, 15, v100
	v_or_b32_e32 v100, v96, v128
	v_add_u32_e32 v105, s8, v105
	v_ashrrev_i32_e32 v101, 31, v100
	v_lshl_or_b32 v98, v112, 2, v105
	v_lshlrev_b64 v[106:107], 12, v[100:101]
	v_ashrrev_i32_e32 v99, 31, v98
	v_lshl_add_u64 v[106:107], s[40:41], 0, v[106:107]
	v_lshl_add_u64 v[110:111], v[98:99], 2, v[106:107]
	s_barrier
	v_add_co_u32_e32 v182, vcc, 0x20000, v110
	s_nop 1
	v_addc_co_u32_e32 v183, vcc, 0, v111, vcc
	global_load_dwordx4 v[184:187], v[182:183], off
	v_add_co_u32_e32 v182, vcc, 0x4000, v182
	s_nop 1
	v_addc_co_u32_e32 v183, vcc, 0, v183, vcc
	global_load_dwordx4 v[188:191], v[182:183], off
	v_add_co_u32_e32 v182, vcc, 0x4000, v182
	s_nop 1
	v_addc_co_u32_e32 v183, vcc, 0, v183, vcc
	global_load_dwordx4 v[192:195], v[182:183], off
	v_add_co_u32_e32 v182, vcc, 0x4000, v182
	s_nop 1
	v_addc_co_u32_e32 v183, vcc, 0, v183, vcc
	global_load_dwordx4 v[116:119], v[182:183], off
	v_add_co_u32_e32 v182, vcc, 0x4000, v182
	s_nop 1
	v_addc_co_u32_e32 v183, vcc, 0, v183, vcc
	global_load_dwordx4 v[120:123], v[182:183], off
	v_add_co_u32_e32 v182, vcc, 0x4000, v182
	s_nop 1
	v_addc_co_u32_e32 v183, vcc, 0, v183, vcc
	global_load_dwordx4 v[124:127], v[182:183], off
	v_add_co_u32_e32 v182, vcc, 0x4000, v182
	s_nop 1
	v_addc_co_u32_e32 v183, vcc, 0, v183, vcc
	global_load_dwordx4 v[130:133], v[182:183], off
	v_add_co_u32_e32 v182, vcc, 0x4000, v182
	s_nop 1
	v_addc_co_u32_e32 v183, vcc, 0, v183, vcc
	global_load_dwordx4 v[134:137], v[182:183], off
	s_movk_i32 s2, 0x2400
	s_cmp_lt_i32 s5, 22
	v_mul_lo_u32 v97, v103, s2
	s_cselect_b64 s[2:3], -1, 0
	s_cmp_gt_i32 s5, 21
	s_movk_i32 s5, 0x110
	v_and_b32_e32 v103, 16, v104
	v_mad_u32_u24 v104, v102, s5, v97
	v_add_u32_e32 v113, 0xfffff000, v96
	v_cndmask_b32_e64 v102, 0, 1, s[2:3]
	s_cselect_b64 s[2:3], -1, 0
	s_add_i32 s7, s4, 0xfffff000
	v_add_u32_e32 v104, v104, v103
	ds_write_b128 v104, v[64:67]
	ds_write_b128 v104, v[68:71] offset:32
	ds_write_b128 v104, v[72:75] offset:64
	ds_write_b128 v104, v[76:79] offset:96
	ds_write_b128 v104, v[80:83] offset:128
	ds_write_b128 v104, v[84:87] offset:160
	ds_write_b128 v104, v[88:91] offset:192
	ds_write_b128 v104, v[92:95] offset:224
	v_xor_b32_e32 v64, s7, v113
	s_movk_i32 s4, 0x400
	v_lshl_or_b32 v97, v112, 4, v97
	v_cmp_gt_u32_e32 vcc, s4, v64
	v_mad_u32_u24 v115, v128, s5, v97
	s_and_b64 s[4:5], s[2:3], vcc
	v_cndmask_b32_e64 v71, 0, 1, s[4:5]
	s_movk_i32 s4, 0x1000
	v_cmp_gt_i32_e32 vcc, s4, v100
	v_subrev_u32_e32 v114, s8, v98
	v_lshl_add_u32 v103, v114, 2, v167
	v_cndmask_b32_e32 v64, v71, v102, vcc
	v_and_b32_e32 v64, 1, v64
	v_cmp_eq_u32_e32 vcc, 1, v64
	v_ashrrev_i32_e32 v68, 6, v105
	s_mov_b32 s4, 0xc000
	v_cndmask_b32_e64 v64, v171, 0, vcc
	v_add_u32_e32 v70, v103, v64
	ds_read_b128 v[64:67], v115
	ds_read_b128 v[72:75], v70
	v_cmp_eq_u32_e64 s[36:37], 0, v112
	v_mad_i64_i32 v[68:69], s[4:5], v68, s4, 0
	s_and_b64 vcc, exec, s[0:1]
	s_waitcnt lgkmcnt(0)
	v_pk_fma_f32 v[66:67], v[66:67], v[74:75], v[200:201]
	v_pk_fma_f32 v[64:65], v[64:65], v[72:73], v[198:199]
	global_store_dwordx4 v[110:111], v[64:67], off
	s_cbranch_vccnz .LBB0_686
	ds_read_b128 v[72:75], v70 offset:2048
	v_lshlrev_b64 v[76:77], 10, v[100:101]
	v_lshl_add_u64 v[76:77], v[76:77], 1, s[42:43]
	v_lshl_add_u64 v[76:77], v[98:99], 1, v[76:77]
	s_waitcnt lgkmcnt(0)
	v_pk_mul_f32 v[72:73], v[64:65], v[72:73]
	v_pk_mul_f32 v[64:65], v[64:65], v[64:65]
	v_pk_mul_f32 v[74:75], v[66:67], v[74:75]
	v_pk_mul_f32 v[66:67], v[66:67], v[66:67]
	v_add_f32_e32 v64, v64, v65
	v_add_f32_e32 v64, v66, v64
	v_add_f32_e32 v64, v67, v64
	v_cvt_pk_bf16_f32 v72, v72, v73
	v_cvt_pk_bf16_f32 v73, v74, v75
	v_add_f32_dpp v64, v64, v64 quad_perm:[1,0,3,2] row_mask:0xf bank_mask:0xf bound_ctrl:1
	global_store_dwordx2 v[76:77], v[72:73], off
	s_nop 0
	v_add_f32_dpp v64, v64, v64 quad_perm:[2,3,0,1] row_mask:0xf bank_mask:0xf bound_ctrl:1
	s_nop 1
	v_add_f32_dpp v64, v64, v64 row_half_mirror row_mask:0xf bank_mask:0xf bound_ctrl:1
	s_nop 1
	v_mov_b32_dpp v65, v64 row_mirror row_mask:0xf bank_mask:0xf bound_ctrl:1
	s_and_saveexec_b64 s[4:5], s[36:37]
	s_cbranch_execz .LBB0_685
	v_lshl_add_u64 v[66:67], s[52:53], 0, v[68:69]
	v_lshl_add_u64 v[66:67], v[100:101], 2, v[66:67]
	v_add_f32_e32 v64, v64, v65
	global_store_dword v[66:67], v64, off

.LBB0_1222:
	s_waitcnt vmcnt(0)
	ds_write_b32 v2, v246
	v_ashrrev_i32_e32 v103, 6, v100
	v_lshrrev_b32_e32 v0, 30, v103
	v_add_u32_e32 v0, v103, v0
	v_ashrrev_i32_e32 v10, 2, v0
	v_mul_i32_i24_e32 v0, 4, v10
	v_ashrrev_i32_e32 v6, 3, v100
	v_sub_u32_e32 v11, v103, v0
	v_lshrrev_b32_e32 v13, 4, v100
	v_add_u32_e32 v0, s4, v6
	v_xor_b32_e32 v7, v13, v100
	v_ashrrev_i32_e32 v1, 31, v0
	v_lshlrev_b64 v[0:1], 11, v[0:1]
	v_lshlrev_b32_e32 v7, 4, v7
	v_lshlrev_b32_e32 v109, 4, v100
	s_and_b32 s8, s2, 0xffffff00
	v_lshl_add_u64 v[4:5], s[46:47], 0, v[0:1]
	v_and_b32_e32 v128, 0x70, v7
	v_readfirstlane_b32 s2, v109
	v_add_u32_e32 v14, 0x2000, v109
	v_lshl_add_u64 v[4:5], v[4:5], 0, v[128:129]
	s_mov_b32 m0, s2
	s_mov_b64 s[10:11], 0x20000
	v_readfirstlane_b32 s2, v14
	ds_write_b32 v2, v3 offset:2048
	v_lshl_add_u64 v[2:3], v[4:5], 0, s[10:11]
	s_mov_b32 m0, s2
	s_mov_b64 s[12:13], 0x40000
	v_lshl_add_u64 v[2:3], v[4:5], 0, s[12:13]
	v_add_u32_e32 v4, 0x4000, v109
	v_add_u32_e32 v6, s8, v6
	v_readfirstlane_b32 s2, v4
	v_ashrrev_i32_e32 v7, 31, v6
	s_mov_b32 m0, s2
	v_lshlrev_b64 v[6:7], 11, v[6:7]
	v_add_u32_e32 v2, 0x6000, v109
	v_lshl_add_u64 v[8:9], s[56:57], 0, v[6:7]
	v_readfirstlane_b32 s2, v2
	v_add_u32_e32 v4, 0x8000, v109
	v_lshl_add_u64 v[8:9], v[8:9], 0, v[128:129]
	s_mov_b32 m0, s2
	v_readfirstlane_b32 s2, v4
	v_add_u32_e32 v4, 0xa000, v109
	v_lshl_add_u64 v[2:3], v[8:9], 0, s[10:11]
	s_mov_b32 m0, s2
	v_readfirstlane_b32 s2, v4
	v_lshl_add_u64 v[2:3], v[8:9], 0, s[12:13]
	s_mov_b32 m0, s2
	s_mov_b64 s[2:3], 0x60000
	v_add_u32_e32 v4, 0xc000, v109
	v_lshl_add_u64 v[2:3], v[8:9], 0, s[2:3]
	v_readfirstlane_b32 s2, v4
	s_mov_b32 m0, s2
	v_and_b32_e32 v102, 31, v100
	v_lshlrev_b32_e32 v105, 6, v11
	v_or_b32_e32 v3, v105, v102
	v_mul_i32_i24_e32 v106, 0x60, v10
	v_bfe_u32 v12, v100, 5, 1
	v_lshrrev_b32_e32 v104, 1, v100
	v_lshlrev_b32_e32 v112, 7, v3
	v_or_b32_e32 v3, v106, v102
	v_bfe_u32 v2, v100, 1, 3
	v_lshlrev_b32_e32 v113, 7, v3
	v_bitop3_b32 v3, v12, v104, 7 bitop3:0x78
	v_lshlrev_b32_e32 v111, 4, v3
	v_bitop3_b32 v3, v12, v2, 2 bitop3:0x36
	v_lshlrev_b32_e32 v110, 4, v3
	v_bitop3_b32 v3, v12, v2, 4 bitop3:0x36
	v_bitop3_b32 v2, v12, v2, 6 bitop3:0x36
	v_lshlrev_b32_e32 v107, 4, v2
	v_bitop3_b32 v2, v13, 7, v100 bitop3:0x48
	v_lshlrev_b32_e32 v2, 4, v2
	v_or_b32_e32 v6, v6, v2
	v_or_b32_e32 v0, v0, v2
	v_and_b32_e32 v101, 63, v100
	v_lshlrev_b32_e32 v108, 4, v3
	v_add_u32_e32 v114, 0x6000, v112
	v_lshl_add_u64 v[96:97], s[58:59], 0, v[6:7]
	v_lshl_add_u64 v[98:99], s[14:15], 0, v[0:1]
	s_mov_b32 s7, 0
	s_mov_b64 s[2:3], 0
	v_mov_b32_e32 v33, v32
	v_mov_b32_e32 v34, v32
	v_mov_b32_e32 v35, v32
	v_mov_b32_e32 v36, v32
	v_mov_b32_e32 v37, v32
	v_mov_b32_e32 v38, v32
	v_mov_b32_e32 v39, v32
	v_mov_b32_e32 v40, v32
	v_mov_b32_e32 v41, v32
	v_mov_b32_e32 v42, v32
	v_mov_b32_e32 v43, v32
	v_mov_b32_e32 v44, v32
	v_mov_b32_e32 v45, v32
	v_mov_b32_e32 v46, v32
	v_mov_b32_e32 v47, v32
	v_mov_b32_e32 v64, v32
	v_mov_b32_e32 v65, v32
	v_mov_b32_e32 v66, v32
	v_mov_b32_e32 v67, v32
	v_mov_b32_e32 v68, v32
	v_mov_b32_e32 v69, v32
	v_mov_b32_e32 v70, v32
	v_mov_b32_e32 v71, v32
	v_mov_b32_e32 v72, v32
	v_mov_b32_e32 v73, v32
	v_mov_b32_e32 v74, v32
	v_mov_b32_e32 v75, v32
	v_mov_b32_e32 v76, v32
	v_mov_b32_e32 v77, v32
	v_mov_b32_e32 v78, v32
	v_mov_b32_e32 v79, v32
	v_mov_b32_e32 v0, v32
	v_mov_b32_e32 v1, v32
	v_mov_b32_e32 v2, v32
	v_mov_b32_e32 v3, v32
	v_mov_b32_e32 v4, v32
	v_mov_b32_e32 v5, v32
	v_mov_b32_e32 v6, v32
	v_mov_b32_e32 v7, v32
	v_mov_b32_e32 v8, v32
	v_mov_b32_e32 v9, v32
	v_mov_b32_e32 v10, v32
	v_mov_b32_e32 v11, v32
	v_mov_b32_e32 v12, v32
	v_mov_b32_e32 v13, v32
	v_mov_b32_e32 v14, v32
	v_mov_b32_e32 v15, v32
	v_mov_b32_e32 v80, v32
	v_mov_b32_e32 v81, v32
	v_mov_b32_e32 v82, v32
	v_mov_b32_e32 v83, v32
	v_mov_b32_e32 v84, v32
	v_mov_b32_e32 v85, v32
	v_mov_b32_e32 v86, v32
	v_mov_b32_e32 v87, v32
	v_mov_b32_e32 v88, v32
	v_mov_b32_e32 v89, v32
	v_mov_b32_e32 v90, v32
	v_mov_b32_e32 v91, v32
	v_mov_b32_e32 v92, v32
	v_mov_b32_e32 v93, v32
	v_mov_b32_e32 v94, v32
	v_mov_b32_e32 v95, v32
	v_mov_b32_e32 v48, v32
	v_mov_b32_e32 v49, v32
	v_mov_b32_e32 v50, v32
	v_mov_b32_e32 v51, v32
	v_mov_b32_e32 v52, v32
	v_mov_b32_e32 v53, v32
	v_mov_b32_e32 v54, v32
	v_mov_b32_e32 v55, v32
	v_mov_b32_e32 v56, v32
	v_mov_b32_e32 v57, v32
	v_mov_b32_e32 v58, v32
	v_mov_b32_e32 v59, v32
	v_mov_b32_e32 v60, v32
	v_mov_b32_e32 v61, v32
	v_mov_b32_e32 v62, v32
	v_mov_b32_e32 v63, v32
	v_mov_b32_e32 v16, v32
	v_mov_b32_e32 v17, v32
	v_mov_b32_e32 v18, v32
	v_mov_b32_e32 v19, v32
	v_mov_b32_e32 v20, v32
	v_mov_b32_e32 v21, v32
	v_mov_b32_e32 v22, v32
	v_mov_b32_e32 v23, v32
	v_mov_b32_e32 v24, v32
	v_mov_b32_e32 v25, v32
	v_mov_b32_e32 v26, v32
	v_mov_b32_e32 v27, v32
	v_mov_b32_e32 v28, v32
	v_mov_b32_e32 v29, v32
	v_mov_b32_e32 v30, v32
	v_mov_b32_e32 v31, v32
	s_mov_b64 s[12:13], 0x8794080
	s_mov_b64 s[16:17], 0x87b4080
	s_mov_b64 s[18:19], 0x87d4080
	v_add_u32_e32 v243, s4, v106
	v_lshrrev_b32_e32 v244, 4, v101
	v_or_b32_e32 v243, v243, v244
	v_and_b32_e32 v244, 15, v100
	v_add_u32_e32 v245, s8, v105
	v_lshl_or_b32 v244, v244, 2, v245
	v_lshlrev_b32_e32 v243, 12, v243
	v_lshl_add_u32 v243, v244, 2, v243
	global_load_dwordx4 v[198:201], v243, s[42:43]
	v_add_u32_e32 v243, 0x4000, v243
	global_load_dwordx4 v[202:205], v243, s[42:43]
	v_add_u32_e32 v243, 0x4000, v243
	global_load_dwordx4 v[206:209], v243, s[42:43]
	v_add_u32_e32 v243, 0x4000, v243
	global_load_dwordx4 v[210:213], v243, s[42:43]
	v_add_u32_e32 v243, 0x4000, v243
	global_load_dwordx4 v[214:217], v243, s[42:43]
	v_add_u32_e32 v243, 0x4000, v243
	global_load_dwordx4 v[218:221], v243, s[42:43]
	v_add_u32_e32 v243, 0x4000, v243
	global_load_dwordx4 v[222:225], v243, s[42:43]
	v_add_u32_e32 v243, 0x4000, v243
	global_load_dwordx4 v[226:229], v243, s[42:43]
	s_add_i32 s9, s7, 1
	s_bitcmp1_b32 s9, 0
	s_cselect_b32 s10, 0xe000, 0
	v_add_u32_e32 v115, s10, v109
	v_lshl_add_u64 v[116:117], v[98:99], 0, s[2:3]
	v_readfirstlane_b32 s10, v115
	v_add_u32_e32 v120, 0x2000, v115
	v_lshl_add_u64 v[118:119], v[116:117], 0, s[12:13]
	s_mov_b32 m0, s10
	v_readfirstlane_b32 s10, v120
	s_waitcnt vmcnt(8)
	s_waitcnt vmcnt(8) lgkmcnt(0)
	s_barrier
	s_branch .Lbody_LBB01223

.Lbody_LBB01223:
	global_load_lds_dwordx4 v[118:119], off
	v_lshl_add_u64 v[118:119], v[116:117], 0, s[16:17]
	s_mov_b32 m0, s10
	v_lshl_add_u64 v[116:117], v[116:117], 0, s[18:19]
	global_load_lds_dwordx4 v[118:119], off
	v_add_u32_e32 v118, 0x4000, v115
	v_add_u32_e32 v120, 0x6000, v115
	v_readfirstlane_b32 s10, v118
	s_mov_b32 m0, s10
	s_mov_b64 s[10:11], 0x5f14080
	global_load_lds_dwordx4 v[116:117], off
	v_lshl_add_u64 v[116:117], v[96:97], 0, s[2:3]
	v_lshl_add_u64 v[118:119], v[116:117], 0, s[10:11]
	v_readfirstlane_b32 s10, v120
	s_mov_b32 m0, s10
	s_mov_b64 s[10:11], 0x5f34080
	v_add_u32_e32 v120, 0x8000, v115
	global_load_lds_dwordx4 v[118:119], off
	v_lshl_add_u64 v[118:119], v[116:117], 0, s[10:11]
	v_readfirstlane_b32 s10, v120
	s_mov_b32 m0, s10
	s_mov_b64 s[10:11], 0x5f54080
	v_add_u32_e32 v120, 0xa000, v115
	global_load_lds_dwordx4 v[118:119], off
	v_lshl_add_u64 v[118:119], v[116:117], 0, s[10:11]
	v_readfirstlane_b32 s10, v120
	s_mov_b32 m0, s10
	s_mov_b64 s[10:11], 0x5f74080
	v_add_u32_e32 v115, 0xc000, v115
	v_lshl_add_u64 v[116:117], v[116:117], 0, s[10:11]
	v_readfirstlane_b32 s10, v115
	global_load_lds_dwordx4 v[118:119], off
	s_mov_b32 m0, s10
	s_nop 0
	global_load_lds_dwordx4 v[116:117], off
	s_bitcmp1_b32 s7, 0
	s_cselect_b32 s7, 0xe000, 0
	v_add_u32_e32 v115, s7, v114
	v_add_u32_e32 v120, v115, v111
	ds_read_b128 v[116:119], v120 offset:0
	v_add_u32_e32 v128, s7, v113
	ds_read_b128 v[120:123], v120 offset:0x1000
	v_add_u32_e32 v134, v128, v111
	ds_read_b128 v[124:127], v134 offset:0
	ds_read_b128 v[130:133], v134 offset:0x1000
	ds_read_b128 v[134:137], v134 offset:0x2000
	v_add_u32_e32 v148, v115, v110
	ds_read_b128 v[144:147], v148 offset:0
	ds_read_b128 v[148:151], v148 offset:0x1000
	v_add_u32_e32 v152, v128, v110
	ds_read_b128 v[182:185], v152 offset:0
	ds_read_b128 v[186:189], v152 offset:0x1000
	ds_read_b128 v[190:193], v152 offset:0x2000
	s_waitcnt lgkmcnt(5)
	s_nop 0
	v_mfma_f32_32x32x16_bf16 v[64:79], v[116:119], v[124:127], v[64:79]
	v_mfma_f32_32x32x16_bf16 v[32:47], v[116:119], v[130:133], v[32:47]
	v_mfma_f32_32x32x16_bf16 v[0:15], v[116:119], v[134:137], v[0:15]
	v_mfma_f32_32x32x16_bf16 v[80:95], v[120:123], v[124:127], v[80:95]
	v_mfma_f32_32x32x16_bf16 v[48:63], v[120:123], v[130:133], v[48:63]
	v_mfma_f32_32x32x16_bf16 v[16:31], v[120:123], v[134:137], v[16:31]
	v_add_u32_e32 v120, v115, v108
	ds_read_b128 v[116:119], v120 offset:0
	ds_read_b128 v[120:123], v120 offset:0x1000
	v_add_u32_e32 v134, v128, v108
	ds_read_b128 v[124:127], v134 offset:0
	ds_read_b128 v[130:133], v134 offset:0x1000
	ds_read_b128 v[134:137], v134 offset:0x2000
	s_waitcnt lgkmcnt(5)
	s_nop 0
	v_mfma_f32_32x32x16_bf16 v[64:79], v[144:147], v[182:185], v[64:79]
	v_mfma_f32_32x32x16_bf16 v[32:47], v[144:147], v[186:189], v[32:47]
	v_mfma_f32_32x32x16_bf16 v[0:15], v[144:147], v[190:193], v[0:15]
	v_mfma_f32_32x32x16_bf16 v[80:95], v[148:151], v[182:185], v[80:95]
	v_mfma_f32_32x32x16_bf16 v[48:63], v[148:151], v[186:189], v[48:63]
	v_mfma_f32_32x32x16_bf16 v[16:31], v[148:151], v[190:193], v[16:31]
	v_add_u32_e32 v115, v115, v107
	ds_read_b128 v[144:147], v115 offset:0
	ds_read_b128 v[148:151], v115 offset:0x1000
	v_add_u32_e32 v115, v128, v107
	ds_read_b128 v[182:185], v115 offset:0
	ds_read_b128 v[186:189], v115 offset:0x1000
	ds_read_b128 v[190:193], v115 offset:0x2000
	s_waitcnt lgkmcnt(5)
	s_nop 0
	v_mfma_f32_32x32x16_bf16 v[64:79], v[116:119], v[124:127], v[64:79]
	v_mfma_f32_32x32x16_bf16 v[32:47], v[116:119], v[130:133], v[32:47]
	v_mfma_f32_32x32x16_bf16 v[0:15], v[116:119], v[134:137], v[0:15]
	v_mfma_f32_32x32x16_bf16 v[80:95], v[120:123], v[124:127], v[80:95]
	v_mfma_f32_32x32x16_bf16 v[48:63], v[120:123], v[130:133], v[48:63]
	v_mfma_f32_32x32x16_bf16 v[16:31], v[120:123], v[134:137], v[16:31]
	s_waitcnt lgkmcnt(0)
	s_nop 0
	v_mfma_f32_32x32x16_bf16 v[64:79], v[144:147], v[182:185], v[64:79]
	v_mfma_f32_32x32x16_bf16 v[32:47], v[144:147], v[186:189], v[32:47]
	v_mfma_f32_32x32x16_bf16 v[0:15], v[144:147], v[190:193], v[0:15]
	v_mfma_f32_32x32x16_bf16 v[80:95], v[148:151], v[182:185], v[80:95]
	v_mfma_f32_32x32x16_bf16 v[48:63], v[148:151], v[186:189], v[48:63]
	v_mfma_f32_32x32x16_bf16 v[16:31], v[148:151], v[190:193], v[16:31]
	s_add_u32 s2, s2, 0x80
	s_addc_u32 s3, s3, 0
	s_cmpk_eq_i32 s2, 0x780
	s_mov_b32 s7, s9
	s_cbranch_scc0 .LBB0_1223
	s_waitcnt vmcnt(0)
	s_waitcnt vmcnt(0) lgkmcnt(0)
	s_barrier
	v_add_u32_e32 v109, 0x14000, v112
	v_add_u32_e32 v112, v109, v111
	ds_read_b128 v[96:99], v112 offset:0
	v_add_u32_e32 v128, 0xe000, v113
	ds_read_b128 v[112:115], v112 offset:0x1000
	v_add_u32_e32 v111, v128, v111
	ds_read_b128 v[116:119], v111 offset:0
	ds_read_b128 v[120:123], v111 offset:0x1000
	ds_read_b128 v[124:127], v111 offset:0x2000
	v_add_u32_e32 v111, v109, v110
	ds_read_b128 v[130:133], v111 offset:0
	ds_read_b128 v[134:137], v111 offset:0x1000
	v_add_u32_e32 v110, v128, v110
	ds_read_b128 v[144:147], v110 offset:0
	ds_read_b128 v[148:151], v110 offset:0x1000
	ds_read_b128 v[182:185], v110 offset:0x2000
	s_waitcnt lgkmcnt(5)
	s_nop 0
	v_mfma_f32_32x32x16_bf16 v[64:79], v[96:99], v[116:119], v[64:79]
	v_mfma_f32_32x32x16_bf16 v[32:47], v[96:99], v[120:123], v[32:47]
	v_mfma_f32_32x32x16_bf16 v[0:15], v[96:99], v[124:127], v[0:15]
	v_mfma_f32_32x32x16_bf16 v[48:63], v[112:115], v[120:123], v[48:63]
	v_mfma_f32_32x32x16_bf16 v[16:31], v[112:115], v[124:127], v[16:31]
	v_mfma_f32_32x32x16_bf16 v[80:95], v[112:115], v[116:119], v[80:95]
	v_add_u32_e32 v110, v109, v108
	ds_read_b128 v[96:99], v110 offset:0
	ds_read_b128 v[110:113], v110 offset:0x1000
	v_add_u32_e32 v108, v128, v108
	ds_read_b128 v[114:117], v108 offset:0
	ds_read_b128 v[118:121], v108 offset:0x1000
	ds_read_b128 v[122:125], v108 offset:0x2000
	s_waitcnt lgkmcnt(5)
	s_nop 0
	v_mfma_f32_32x32x16_bf16 v[64:79], v[130:133], v[144:147], v[64:79]
	v_mfma_f32_32x32x16_bf16 v[32:47], v[130:133], v[148:151], v[32:47]
	v_mfma_f32_32x32x16_bf16 v[0:15], v[130:133], v[182:185], v[0:15]
	v_mfma_f32_32x32x16_bf16 v[48:63], v[134:137], v[148:151], v[48:63]
	v_mfma_f32_32x32x16_bf16 v[16:31], v[134:137], v[182:185], v[16:31]
	v_mfma_f32_32x32x16_bf16 v[80:95], v[134:137], v[144:147], v[80:95]
	v_add_u32_e32 v108, v109, v107
	ds_read_b128 v[130:133], v108 offset:0
	ds_read_b128 v[134:137], v108 offset:0x1000
	v_add_u32_e32 v107, v128, v107
	ds_read_b128 v[144:147], v107 offset:0
	ds_read_b128 v[148:151], v107 offset:0x1000
	ds_read_b128 v[182:185], v107 offset:0x2000
	s_waitcnt lgkmcnt(5)
	s_nop 0
	v_mfma_f32_32x32x16_bf16 v[64:79], v[96:99], v[114:117], v[64:79]
	v_mfma_f32_32x32x16_bf16 v[32:47], v[96:99], v[118:121], v[32:47]
	v_mfma_f32_32x32x16_bf16 v[0:15], v[96:99], v[122:125], v[0:15]
	v_mfma_f32_32x32x16_bf16 v[48:63], v[110:113], v[118:121], v[48:63]
	v_mfma_f32_32x32x16_bf16 v[16:31], v[110:113], v[122:125], v[16:31]
	v_mfma_f32_32x32x16_bf16 v[80:95], v[110:113], v[114:117], v[80:95]
	s_waitcnt lgkmcnt(0)
	s_nop 0
	v_mfma_f32_32x32x16_bf16 v[64:79], v[130:133], v[144:147], v[64:79]
	v_mfma_f32_32x32x16_bf16 v[32:47], v[130:133], v[148:151], v[32:47]
	v_mfma_f32_32x32x16_bf16 v[0:15], v[130:133], v[182:185], v[0:15]
	v_mfma_f32_32x32x16_bf16 v[48:63], v[134:137], v[148:151], v[48:63]
	v_mfma_f32_32x32x16_bf16 v[16:31], v[134:137], v[182:185], v[16:31]
	v_mfma_f32_32x32x16_bf16 v[80:95], v[134:137], v[144:147], v[80:95]
	v_add_u32_e32 v96, s4, v106
	v_lshrrev_b32_e32 v128, 4, v101
	v_and_b32_e32 v112, 15, v100
	v_or_b32_e32 v100, v96, v128
	v_add_u32_e32 v105, s8, v105
	v_ashrrev_i32_e32 v101, 31, v100
	v_lshl_or_b32 v98, v112, 2, v105
	v_lshlrev_b64 v[106:107], 12, v[100:101]
	v_ashrrev_i32_e32 v99, 31, v98
	v_lshl_add_u64 v[106:107], s[42:43], 0, v[106:107]
	v_lshl_add_u64 v[110:111], v[98:99], 2, v[106:107]
	s_barrier
	v_add_co_u32_e32 v182, vcc, 0x20000, v110
	s_nop 1
	v_addc_co_u32_e32 v183, vcc, 0, v111, vcc
	global_load_dwordx4 v[184:187], v[182:183], off
	v_add_co_u32_e32 v182, vcc, 0x4000, v182
	s_nop 1
	v_addc_co_u32_e32 v183, vcc, 0, v183, vcc
	global_load_dwordx4 v[188:191], v[182:183], off
	v_add_co_u32_e32 v182, vcc, 0x4000, v182
	s_nop 1
	v_addc_co_u32_e32 v183, vcc, 0, v183, vcc
	global_load_dwordx4 v[192:195], v[182:183], off
	v_add_co_u32_e32 v182, vcc, 0x4000, v182
	s_nop 1
	v_addc_co_u32_e32 v183, vcc, 0, v183, vcc
	global_load_dwordx4 v[116:119], v[182:183], off
	v_add_co_u32_e32 v182, vcc, 0x4000, v182
	s_nop 1
	v_addc_co_u32_e32 v183, vcc, 0, v183, vcc
	global_load_dwordx4 v[120:123], v[182:183], off
	v_add_co_u32_e32 v182, vcc, 0x4000, v182
	s_nop 1
	v_addc_co_u32_e32 v183, vcc, 0, v183, vcc
	global_load_dwordx4 v[124:127], v[182:183], off
	v_add_co_u32_e32 v182, vcc, 0x4000, v182
	s_nop 1
	v_addc_co_u32_e32 v183, vcc, 0, v183, vcc
	global_load_dwordx4 v[130:133], v[182:183], off
	v_add_co_u32_e32 v182, vcc, 0x4000, v182
	s_nop 1
	v_addc_co_u32_e32 v183, vcc, 0, v183, vcc
	global_load_dwordx4 v[134:137], v[182:183], off
	s_movk_i32 s2, 0x2400
	s_cmp_lt_i32 s5, 22
	v_mul_lo_u32 v97, v103, s2
	s_cselect_b64 s[2:3], -1, 0
	s_cmp_gt_i32 s5, 21
	s_movk_i32 s5, 0x110
	v_and_b32_e32 v103, 16, v104
	v_mad_u32_u24 v104, v102, s5, v97
	v_add_u32_e32 v113, 0xfffff000, v96
	v_cndmask_b32_e64 v102, 0, 1, s[2:3]
	s_cselect_b64 s[2:3], -1, 0
	s_add_i32 s7, s4, 0xfffff000
	v_add_u32_e32 v104, v104, v103
	ds_write_b128 v104, v[64:67]
	ds_write_b128 v104, v[68:71] offset:32
	ds_write_b128 v104, v[72:75] offset:64
	ds_write_b128 v104, v[76:79] offset:96
	ds_write_b128 v104, v[80:83] offset:128
	ds_write_b128 v104, v[84:87] offset:160
	ds_write_b128 v104, v[88:91] offset:192
	ds_write_b128 v104, v[92:95] offset:224
	v_xor_b32_e32 v64, s7, v113
	s_movk_i32 s4, 0x400
	v_lshl_or_b32 v97, v112, 4, v97
	v_cmp_gt_u32_e32 vcc, s4, v64
	v_mad_u32_u24 v115, v128, s5, v97
	s_and_b64 s[4:5], s[2:3], vcc
	v_cndmask_b32_e64 v71, 0, 1, s[4:5]
	s_movk_i32 s4, 0x1000
	v_cmp_gt_i32_e32 vcc, s4, v100
	v_subrev_u32_e32 v114, s8, v98
	v_lshl_add_u32 v103, v114, 2, v167
	v_cndmask_b32_e32 v64, v71, v102, vcc
	v_and_b32_e32 v64, 1, v64
	v_cmp_eq_u32_e32 vcc, 1, v64
	v_ashrrev_i32_e32 v68, 6, v105
	s_mov_b32 s4, 0xc000
	v_cndmask_b32_e64 v64, v171, 0, vcc
	v_add_u32_e32 v70, v103, v64
	ds_read_b128 v[64:67], v115
	ds_read_b128 v[72:75], v70
	v_cmp_eq_u32_e64 s[40:41], 0, v112
	v_mad_i64_i32 v[68:69], s[4:5], v68, s4, 0
	s_and_b64 vcc, exec, s[0:1]
	s_waitcnt lgkmcnt(0)
	v_pk_fma_f32 v[66:67], v[66:67], v[74:75], v[200:201]
	v_pk_fma_f32 v[64:65], v[64:65], v[72:73], v[198:199]
	global_store_dwordx4 v[110:111], v[64:67], off
	s_cbranch_vccnz .LBB0_1228
	ds_read_b128 v[72:75], v70 offset:2048
	v_lshlrev_b64 v[76:77], 10, v[100:101]
	v_lshl_add_u64 v[76:77], v[76:77], 1, s[44:45]
	v_lshl_add_u64 v[76:77], v[98:99], 1, v[76:77]
	s_waitcnt lgkmcnt(0)
	v_pk_mul_f32 v[72:73], v[64:65], v[72:73]
	v_pk_mul_f32 v[64:65], v[64:65], v[64:65]
	v_pk_mul_f32 v[74:75], v[66:67], v[74:75]
	v_pk_mul_f32 v[66:67], v[66:67], v[66:67]
	v_add_f32_e32 v64, v64, v65
	v_add_f32_e32 v64, v66, v64
	v_add_f32_e32 v64, v67, v64
	v_cvt_pk_bf16_f32 v72, v72, v73
	v_cvt_pk_bf16_f32 v73, v74, v75
	v_add_f32_dpp v64, v64, v64 quad_perm:[1,0,3,2] row_mask:0xf bank_mask:0xf bound_ctrl:1
	global_store_dwordx2 v[76:77], v[72:73], off
	s_nop 0
	v_add_f32_dpp v64, v64, v64 quad_perm:[2,3,0,1] row_mask:0xf bank_mask:0xf bound_ctrl:1
	s_nop 1
	v_add_f32_dpp v64, v64, v64 row_half_mirror row_mask:0xf bank_mask:0xf bound_ctrl:1
	s_nop 1
	v_mov_b32_dpp v65, v64 row_mirror row_mask:0xf bank_mask:0xf bound_ctrl:1
	s_and_saveexec_b64 s[4:5], s[40:41]
	s_cbranch_execz .LBB0_1227
	v_lshl_add_u64 v[66:67], s[48:49], 0, v[68:69]
	v_lshl_add_u64 v[66:67], v[100:101], 2, v[66:67]
	v_add_f32_e32 v64, v64, v65
	global_store_dword v[66:67], v64, off

.LBB0_1433:
	s_waitcnt vmcnt(0)
	ds_write_b32 v2, v246
	v_ashrrev_i32_e32 v103, 6, v100
	v_lshrrev_b32_e32 v0, 30, v103
	v_add_u32_e32 v0, v103, v0
	v_ashrrev_i32_e32 v10, 2, v0
	v_mul_i32_i24_e32 v0, 4, v10
	v_ashrrev_i32_e32 v6, 3, v100
	v_sub_u32_e32 v11, v103, v0
	v_lshrrev_b32_e32 v13, 4, v100
	v_add_u32_e32 v0, s4, v6
	v_xor_b32_e32 v7, v13, v100
	v_ashrrev_i32_e32 v1, 31, v0
	v_lshlrev_b64 v[0:1], 13, v[0:1]
	v_lshlrev_b32_e32 v7, 4, v7
	v_lshlrev_b32_e32 v109, 4, v100
	s_and_b32 s8, s2, 0xffffff00
	v_lshl_add_u64 v[4:5], s[52:53], 0, v[0:1]
	v_and_b32_e32 v128, 0x70, v7
	v_readfirstlane_b32 s2, v109
	v_add_u32_e32 v14, 0x2000, v109
	v_lshl_add_u64 v[4:5], v[4:5], 0, v[128:129]
	s_mov_b32 m0, s2
	v_readfirstlane_b32 s2, v14
	ds_write_b32 v2, v3 offset:2048
	v_lshl_add_u64 v[2:3], v[4:5], 0, s[16:17]
	s_mov_b32 m0, s2
	v_add_u32_e32 v6, s8, v6
	v_lshl_add_u64 v[2:3], v[4:5], 0, s[20:21]
	v_add_u32_e32 v4, 0x4000, v109
	v_ashrrev_i32_e32 v7, 31, v6
	v_readfirstlane_b32 s2, v4
	s_mov_b32 m0, s2
	v_lshlrev_b64 v[6:7], 13, v[6:7]
	v_add_u32_e32 v2, 0x6000, v109
	v_lshl_add_u64 v[8:9], s[48:49], 0, v[6:7]
	v_readfirstlane_b32 s2, v2
	v_add_u32_e32 v4, 0x8000, v109
	v_lshl_add_u64 v[8:9], v[8:9], 0, v[128:129]
	s_mov_b32 m0, s2
	v_readfirstlane_b32 s2, v4
	v_add_u32_e32 v4, 0xa000, v109
	v_lshl_add_u64 v[2:3], v[8:9], 0, s[16:17]
	s_mov_b32 m0, s2
	v_readfirstlane_b32 s2, v4
	v_lshl_add_u64 v[2:3], v[8:9], 0, s[20:21]
	s_mov_b32 m0, s2
	s_mov_b64 s[2:3], 0x180000
	v_add_u32_e32 v4, 0xc000, v109
	v_lshl_add_u64 v[2:3], v[8:9], 0, s[2:3]
	v_readfirstlane_b32 s2, v4
	s_mov_b32 m0, s2
	v_and_b32_e32 v102, 31, v100
	v_lshlrev_b32_e32 v105, 6, v11
	v_or_b32_e32 v3, v105, v102
	v_mul_i32_i24_e32 v106, 0x60, v10
	v_bfe_u32 v12, v100, 5, 1
	v_lshrrev_b32_e32 v104, 1, v100
	v_lshlrev_b32_e32 v112, 7, v3
	v_or_b32_e32 v3, v106, v102
	v_bfe_u32 v2, v100, 1, 3
	v_lshlrev_b32_e32 v113, 7, v3
	v_bitop3_b32 v3, v12, v104, 7 bitop3:0x78
	v_lshlrev_b32_e32 v111, 4, v3
	v_bitop3_b32 v3, v12, v2, 2 bitop3:0x36
	v_lshlrev_b32_e32 v110, 4, v3
	v_bitop3_b32 v3, v12, v2, 4 bitop3:0x36
	v_bitop3_b32 v2, v12, v2, 6 bitop3:0x36
	v_lshlrev_b32_e32 v107, 4, v2
	v_bitop3_b32 v2, v13, 7, v100 bitop3:0x48
	v_lshlrev_b32_e32 v2, 4, v2
	v_or_b32_e32 v6, v6, v2
	v_or_b32_e32 v0, v0, v2
	v_and_b32_e32 v101, 63, v100
	v_lshlrev_b32_e32 v108, 4, v3
	v_add_u32_e32 v114, 0x6000, v112
	v_lshl_add_u64 v[96:97], s[60:61], 0, v[6:7]
	v_lshl_add_u64 v[98:99], s[14:15], 0, v[0:1]
	s_mov_b32 s7, 0
	s_mov_b64 s[2:3], 0
	v_mov_b32_e32 v33, v32
	v_mov_b32_e32 v34, v32
	v_mov_b32_e32 v35, v32
	v_mov_b32_e32 v36, v32
	v_mov_b32_e32 v37, v32
	v_mov_b32_e32 v38, v32
	v_mov_b32_e32 v39, v32
	v_mov_b32_e32 v40, v32
	v_mov_b32_e32 v41, v32
	v_mov_b32_e32 v42, v32
	v_mov_b32_e32 v43, v32
	v_mov_b32_e32 v44, v32
	v_mov_b32_e32 v45, v32
	v_mov_b32_e32 v46, v32
	v_mov_b32_e32 v47, v32
	v_mov_b32_e32 v64, v32
	v_mov_b32_e32 v65, v32
	v_mov_b32_e32 v66, v32
	v_mov_b32_e32 v67, v32
	v_mov_b32_e32 v68, v32
	v_mov_b32_e32 v69, v32
	v_mov_b32_e32 v70, v32
	v_mov_b32_e32 v71, v32
	v_mov_b32_e32 v72, v32
	v_mov_b32_e32 v73, v32
	v_mov_b32_e32 v74, v32
	v_mov_b32_e32 v75, v32
	v_mov_b32_e32 v76, v32
	v_mov_b32_e32 v77, v32
	v_mov_b32_e32 v78, v32
	v_mov_b32_e32 v79, v32
	v_mov_b32_e32 v0, v32
	v_mov_b32_e32 v1, v32
	v_mov_b32_e32 v2, v32
	v_mov_b32_e32 v3, v32
	v_mov_b32_e32 v4, v32
	v_mov_b32_e32 v5, v32
	v_mov_b32_e32 v6, v32
	v_mov_b32_e32 v7, v32
	v_mov_b32_e32 v8, v32
	v_mov_b32_e32 v9, v32
	v_mov_b32_e32 v10, v32
	v_mov_b32_e32 v11, v32
	v_mov_b32_e32 v12, v32
	v_mov_b32_e32 v13, v32
	v_mov_b32_e32 v14, v32
	v_mov_b32_e32 v15, v32
	v_mov_b32_e32 v80, v32
	v_mov_b32_e32 v81, v32
	v_mov_b32_e32 v82, v32
	v_mov_b32_e32 v83, v32
	v_mov_b32_e32 v84, v32
	v_mov_b32_e32 v85, v32
	v_mov_b32_e32 v86, v32
	v_mov_b32_e32 v87, v32
	v_mov_b32_e32 v88, v32
	v_mov_b32_e32 v89, v32
	v_mov_b32_e32 v90, v32
	v_mov_b32_e32 v91, v32
	v_mov_b32_e32 v92, v32
	v_mov_b32_e32 v93, v32
	v_mov_b32_e32 v94, v32
	v_mov_b32_e32 v95, v32
	v_mov_b32_e32 v48, v32
	v_mov_b32_e32 v49, v32
	v_mov_b32_e32 v50, v32
	v_mov_b32_e32 v51, v32
	v_mov_b32_e32 v52, v32
	v_mov_b32_e32 v53, v32
	v_mov_b32_e32 v54, v32
	v_mov_b32_e32 v55, v32
	v_mov_b32_e32 v56, v32
	v_mov_b32_e32 v57, v32
	v_mov_b32_e32 v58, v32
	v_mov_b32_e32 v59, v32
	v_mov_b32_e32 v60, v32
	v_mov_b32_e32 v61, v32
	v_mov_b32_e32 v62, v32
	v_mov_b32_e32 v63, v32
	v_mov_b32_e32 v16, v32
	v_mov_b32_e32 v17, v32
	v_mov_b32_e32 v18, v32
	v_mov_b32_e32 v19, v32
	v_mov_b32_e32 v20, v32
	v_mov_b32_e32 v21, v32
	v_mov_b32_e32 v22, v32
	v_mov_b32_e32 v23, v32
	v_mov_b32_e32 v24, v32
	v_mov_b32_e32 v25, v32
	v_mov_b32_e32 v26, v32
	v_mov_b32_e32 v27, v32
	v_mov_b32_e32 v28, v32
	v_mov_b32_e32 v29, v32
	v_mov_b32_e32 v30, v32
	v_mov_b32_e32 v31, v32
	v_add_u32_e32 v243, s4, v106
	v_lshrrev_b32_e32 v244, 4, v101
	v_or_b32_e32 v243, v243, v244
	v_and_b32_e32 v244, 15, v100
	v_add_u32_e32 v245, s8, v105
	v_lshl_or_b32 v244, v244, 2, v245
	v_lshlrev_b32_e32 v243, 12, v243
	v_lshl_add_u32 v243, v244, 2, v243
	global_load_dwordx4 v[198:201], v243, s[40:41]
	v_add_u32_e32 v243, 0x4000, v243
	global_load_dwordx4 v[202:205], v243, s[40:41]
	v_add_u32_e32 v243, 0x4000, v243
	global_load_dwordx4 v[206:209], v243, s[40:41]
	v_add_u32_e32 v243, 0x4000, v243
	global_load_dwordx4 v[210:213], v243, s[40:41]
	v_add_u32_e32 v243, 0x4000, v243
	global_load_dwordx4 v[214:217], v243, s[40:41]
	v_add_u32_e32 v243, 0x4000, v243
	global_load_dwordx4 v[218:221], v243, s[40:41]
	v_add_u32_e32 v243, 0x4000, v243
	global_load_dwordx4 v[222:225], v243, s[40:41]
	v_add_u32_e32 v243, 0x4000, v243
	global_load_dwordx4 v[226:229], v243, s[40:41]
	s_add_i32 s9, s7, 1
	s_bitcmp1_b32 s9, 0
	s_cselect_b32 s10, 0xe000, 0
	v_add_u32_e32 v115, s10, v109
	v_lshl_add_u64 v[116:117], v[98:99], 0, s[2:3]
	s_mov_b64 s[10:11], 0x9f94080
	v_lshl_add_u64 v[118:119], v[116:117], 0, s[10:11]
	v_readfirstlane_b32 s10, v115
	s_mov_b32 m0, s10
	s_mov_b64 s[10:11], 0xa014080
	v_add_u32_e32 v120, 0x2000, v115
	s_waitcnt vmcnt(8)
	s_waitcnt vmcnt(8) lgkmcnt(0)
	s_barrier
	s_branch .Lbody_LBB01434

.Lbody_LBB01434:
	global_load_lds_dwordx4 v[118:119], off
	v_lshl_add_u64 v[118:119], v[116:117], 0, s[10:11]
	v_readfirstlane_b32 s10, v120
	s_mov_b32 m0, s10
	s_mov_b64 s[10:11], 0xa094080
	global_load_lds_dwordx4 v[118:119], off
	v_add_u32_e32 v118, 0x4000, v115
	v_lshl_add_u64 v[116:117], v[116:117], 0, s[10:11]
	v_readfirstlane_b32 s10, v118
	s_mov_b32 m0, s10
	s_mov_b64 s[10:11], 0x3314080
	global_load_lds_dwordx4 v[116:117], off
	v_lshl_add_u64 v[116:117], v[96:97], 0, s[2:3]
	v_add_u32_e32 v120, 0x6000, v115
	v_lshl_add_u64 v[118:119], v[116:117], 0, s[10:11]
	v_readfirstlane_b32 s10, v120
	s_mov_b32 m0, s10
	s_mov_b64 s[10:11], 0x3394080
	v_add_u32_e32 v120, 0x8000, v115
	global_load_lds_dwordx4 v[118:119], off
	v_lshl_add_u64 v[118:119], v[116:117], 0, s[10:11]
	v_readfirstlane_b32 s10, v120
	s_mov_b32 m0, s10
	s_mov_b64 s[10:11], 0x3414080
	v_add_u32_e32 v120, 0xa000, v115
	global_load_lds_dwordx4 v[118:119], off
	v_lshl_add_u64 v[118:119], v[116:117], 0, s[10:11]
	v_readfirstlane_b32 s10, v120
	s_mov_b32 m0, s10
	s_mov_b64 s[10:11], 0x3494080
	v_add_u32_e32 v115, 0xc000, v115
	v_lshl_add_u64 v[116:117], v[116:117], 0, s[10:11]
	v_readfirstlane_b32 s10, v115
	global_load_lds_dwordx4 v[118:119], off
	s_mov_b32 m0, s10
	s_nop 0
	global_load_lds_dwordx4 v[116:117], off
	s_bitcmp1_b32 s7, 0
	s_cselect_b32 s7, 0xe000, 0
	v_add_u32_e32 v115, s7, v114
	v_add_u32_e32 v120, v115, v111
	ds_read_b128 v[116:119], v120 offset:0
	v_add_u32_e32 v128, s7, v113
	ds_read_b128 v[120:123], v120 offset:0x1000
	v_add_u32_e32 v134, v128, v111
	ds_read_b128 v[124:127], v134 offset:0
	ds_read_b128 v[130:133], v134 offset:0x1000
	ds_read_b128 v[134:137], v134 offset:0x2000
	v_add_u32_e32 v148, v115, v110
	ds_read_b128 v[144:147], v148 offset:0
	ds_read_b128 v[148:151], v148 offset:0x1000
	v_add_u32_e32 v152, v128, v110
	ds_read_b128 v[182:185], v152 offset:0
	ds_read_b128 v[186:189], v152 offset:0x1000
	ds_read_b128 v[190:193], v152 offset:0x2000
	s_waitcnt lgkmcnt(5)
	s_nop 0
	v_mfma_f32_32x32x16_bf16 v[64:79], v[116:119], v[124:127], v[64:79]
	v_mfma_f32_32x32x16_bf16 v[32:47], v[116:119], v[130:133], v[32:47]
	v_mfma_f32_32x32x16_bf16 v[0:15], v[116:119], v[134:137], v[0:15]
	v_mfma_f32_32x32x16_bf16 v[80:95], v[120:123], v[124:127], v[80:95]
	v_mfma_f32_32x32x16_bf16 v[48:63], v[120:123], v[130:133], v[48:63]
	v_mfma_f32_32x32x16_bf16 v[16:31], v[120:123], v[134:137], v[16:31]
	v_add_u32_e32 v120, v115, v108
	ds_read_b128 v[116:119], v120 offset:0
	ds_read_b128 v[120:123], v120 offset:0x1000
	v_add_u32_e32 v134, v128, v108
	ds_read_b128 v[124:127], v134 offset:0
	ds_read_b128 v[130:133], v134 offset:0x1000
	ds_read_b128 v[134:137], v134 offset:0x2000
	s_waitcnt lgkmcnt(5)
	s_nop 0
	v_mfma_f32_32x32x16_bf16 v[64:79], v[144:147], v[182:185], v[64:79]
	v_mfma_f32_32x32x16_bf16 v[32:47], v[144:147], v[186:189], v[32:47]
	v_mfma_f32_32x32x16_bf16 v[0:15], v[144:147], v[190:193], v[0:15]
	v_mfma_f32_32x32x16_bf16 v[80:95], v[148:151], v[182:185], v[80:95]
	v_mfma_f32_32x32x16_bf16 v[48:63], v[148:151], v[186:189], v[48:63]
	v_mfma_f32_32x32x16_bf16 v[16:31], v[148:151], v[190:193], v[16:31]
	v_add_u32_e32 v115, v115, v107
	ds_read_b128 v[144:147], v115 offset:0
	ds_read_b128 v[148:151], v115 offset:0x1000
	v_add_u32_e32 v115, v128, v107
	ds_read_b128 v[182:185], v115 offset:0
	ds_read_b128 v[186:189], v115 offset:0x1000
	ds_read_b128 v[190:193], v115 offset:0x2000
	s_waitcnt lgkmcnt(5)
	s_nop 0
	v_mfma_f32_32x32x16_bf16 v[64:79], v[116:119], v[124:127], v[64:79]
	v_mfma_f32_32x32x16_bf16 v[32:47], v[116:119], v[130:133], v[32:47]
	v_mfma_f32_32x32x16_bf16 v[0:15], v[116:119], v[134:137], v[0:15]
	v_mfma_f32_32x32x16_bf16 v[80:95], v[120:123], v[124:127], v[80:95]
	v_mfma_f32_32x32x16_bf16 v[48:63], v[120:123], v[130:133], v[48:63]
	v_mfma_f32_32x32x16_bf16 v[16:31], v[120:123], v[134:137], v[16:31]
	s_waitcnt lgkmcnt(0)
	s_nop 0
	v_mfma_f32_32x32x16_bf16 v[64:79], v[144:147], v[182:185], v[64:79]
	v_mfma_f32_32x32x16_bf16 v[32:47], v[144:147], v[186:189], v[32:47]
	v_mfma_f32_32x32x16_bf16 v[0:15], v[144:147], v[190:193], v[0:15]
	v_mfma_f32_32x32x16_bf16 v[80:95], v[148:151], v[182:185], v[80:95]
	v_mfma_f32_32x32x16_bf16 v[48:63], v[148:151], v[186:189], v[48:63]
	v_mfma_f32_32x32x16_bf16 v[16:31], v[148:151], v[190:193], v[16:31]
	s_add_u32 s2, s2, 0x80
	s_addc_u32 s3, s3, 0
	s_cmpk_eq_i32 s2, 0x1f80
	s_mov_b32 s7, s9
	s_cbranch_scc0 .LBB0_1434
	s_waitcnt vmcnt(0)
	s_waitcnt vmcnt(0) lgkmcnt(0)
	s_barrier
	v_add_u32_e32 v109, 0x14000, v112
	v_add_u32_e32 v112, v109, v111
	ds_read_b128 v[96:99], v112 offset:0
	v_add_u32_e32 v128, 0xe000, v113
	ds_read_b128 v[112:115], v112 offset:0x1000
	v_add_u32_e32 v111, v128, v111
	ds_read_b128 v[116:119], v111 offset:0
	ds_read_b128 v[120:123], v111 offset:0x1000
	ds_read_b128 v[124:127], v111 offset:0x2000
	v_add_u32_e32 v111, v109, v110
	ds_read_b128 v[130:133], v111 offset:0
	ds_read_b128 v[134:137], v111 offset:0x1000
	v_add_u32_e32 v110, v128, v110
	ds_read_b128 v[144:147], v110 offset:0
	ds_read_b128 v[148:151], v110 offset:0x1000
	ds_read_b128 v[182:185], v110 offset:0x2000
	s_waitcnt lgkmcnt(5)
	s_nop 0
	v_mfma_f32_32x32x16_bf16 v[64:79], v[96:99], v[116:119], v[64:79]
	v_mfma_f32_32x32x16_bf16 v[32:47], v[96:99], v[120:123], v[32:47]
	v_mfma_f32_32x32x16_bf16 v[0:15], v[96:99], v[124:127], v[0:15]
	v_mfma_f32_32x32x16_bf16 v[48:63], v[112:115], v[120:123], v[48:63]
	v_mfma_f32_32x32x16_bf16 v[16:31], v[112:115], v[124:127], v[16:31]
	v_mfma_f32_32x32x16_bf16 v[80:95], v[112:115], v[116:119], v[80:95]
	v_add_u32_e32 v110, v109, v108
	ds_read_b128 v[96:99], v110 offset:0
	ds_read_b128 v[110:113], v110 offset:0x1000
	v_add_u32_e32 v108, v128, v108
	ds_read_b128 v[114:117], v108 offset:0
	ds_read_b128 v[118:121], v108 offset:0x1000
	ds_read_b128 v[122:125], v108 offset:0x2000
	s_waitcnt lgkmcnt(5)
	s_nop 0
	v_mfma_f32_32x32x16_bf16 v[64:79], v[130:133], v[144:147], v[64:79]
	v_mfma_f32_32x32x16_bf16 v[32:47], v[130:133], v[148:151], v[32:47]
	v_mfma_f32_32x32x16_bf16 v[0:15], v[130:133], v[182:185], v[0:15]
	v_mfma_f32_32x32x16_bf16 v[48:63], v[134:137], v[148:151], v[48:63]
	v_mfma_f32_32x32x16_bf16 v[16:31], v[134:137], v[182:185], v[16:31]
	v_mfma_f32_32x32x16_bf16 v[80:95], v[134:137], v[144:147], v[80:95]
	v_add_u32_e32 v108, v109, v107
	ds_read_b128 v[130:133], v108 offset:0
	ds_read_b128 v[134:137], v108 offset:0x1000
	v_add_u32_e32 v107, v128, v107
	ds_read_b128 v[144:147], v107 offset:0
	ds_read_b128 v[148:151], v107 offset:0x1000
	ds_read_b128 v[182:185], v107 offset:0x2000
	s_waitcnt lgkmcnt(5)
	s_nop 0
	v_mfma_f32_32x32x16_bf16 v[64:79], v[96:99], v[114:117], v[64:79]
	v_mfma_f32_32x32x16_bf16 v[32:47], v[96:99], v[118:121], v[32:47]
	v_mfma_f32_32x32x16_bf16 v[0:15], v[96:99], v[122:125], v[0:15]
	v_mfma_f32_32x32x16_bf16 v[48:63], v[110:113], v[118:121], v[48:63]
	v_mfma_f32_32x32x16_bf16 v[16:31], v[110:113], v[122:125], v[16:31]
	v_mfma_f32_32x32x16_bf16 v[80:95], v[110:113], v[114:117], v[80:95]
	s_waitcnt lgkmcnt(0)
	s_nop 0
	v_mfma_f32_32x32x16_bf16 v[64:79], v[130:133], v[144:147], v[64:79]
	v_mfma_f32_32x32x16_bf16 v[32:47], v[130:133], v[148:151], v[32:47]
	v_mfma_f32_32x32x16_bf16 v[0:15], v[130:133], v[182:185], v[0:15]
	v_mfma_f32_32x32x16_bf16 v[48:63], v[134:137], v[148:151], v[48:63]
	v_mfma_f32_32x32x16_bf16 v[16:31], v[134:137], v[182:185], v[16:31]
	v_mfma_f32_32x32x16_bf16 v[80:95], v[134:137], v[144:147], v[80:95]
	v_add_u32_e32 v96, s4, v106
	v_lshrrev_b32_e32 v128, 4, v101
	v_and_b32_e32 v112, 15, v100
	v_or_b32_e32 v100, v96, v128
	v_add_u32_e32 v105, s8, v105
	v_ashrrev_i32_e32 v101, 31, v100
	v_lshl_or_b32 v98, v112, 2, v105
	v_lshlrev_b64 v[106:107], 12, v[100:101]
	v_ashrrev_i32_e32 v99, 31, v98
	v_lshl_add_u64 v[106:107], s[40:41], 0, v[106:107]
	v_lshl_add_u64 v[110:111], v[98:99], 2, v[106:107]
	s_barrier
	v_add_co_u32_e32 v182, vcc, 0x20000, v110
	s_nop 1
	v_addc_co_u32_e32 v183, vcc, 0, v111, vcc
	global_load_dwordx4 v[184:187], v[182:183], off
	v_add_co_u32_e32 v182, vcc, 0x4000, v182
	s_nop 1
	v_addc_co_u32_e32 v183, vcc, 0, v183, vcc
	global_load_dwordx4 v[188:191], v[182:183], off
	v_add_co_u32_e32 v182, vcc, 0x4000, v182
	s_nop 1
	v_addc_co_u32_e32 v183, vcc, 0, v183, vcc
	global_load_dwordx4 v[192:195], v[182:183], off
	v_add_co_u32_e32 v182, vcc, 0x4000, v182
	s_nop 1
	v_addc_co_u32_e32 v183, vcc, 0, v183, vcc
	global_load_dwordx4 v[116:119], v[182:183], off
	v_add_co_u32_e32 v182, vcc, 0x4000, v182
	s_nop 1
	v_addc_co_u32_e32 v183, vcc, 0, v183, vcc
	global_load_dwordx4 v[120:123], v[182:183], off
	v_add_co_u32_e32 v182, vcc, 0x4000, v182
	s_nop 1
	v_addc_co_u32_e32 v183, vcc, 0, v183, vcc
	global_load_dwordx4 v[124:127], v[182:183], off
	v_add_co_u32_e32 v182, vcc, 0x4000, v182
	s_nop 1
	v_addc_co_u32_e32 v183, vcc, 0, v183, vcc
	global_load_dwordx4 v[130:133], v[182:183], off
	v_add_co_u32_e32 v182, vcc, 0x4000, v182
	s_nop 1
	v_addc_co_u32_e32 v183, vcc, 0, v183, vcc
	global_load_dwordx4 v[134:137], v[182:183], off
	s_movk_i32 s2, 0x2400
	s_cmp_lt_i32 s5, 22
	v_mul_lo_u32 v97, v103, s2
	s_cselect_b64 s[2:3], -1, 0
	s_cmp_gt_i32 s5, 21
	s_movk_i32 s5, 0x110
	v_and_b32_e32 v103, 16, v104
	v_mad_u32_u24 v104, v102, s5, v97
	v_add_u32_e32 v113, 0xfffff000, v96
	v_cndmask_b32_e64 v102, 0, 1, s[2:3]
	s_cselect_b64 s[2:3], -1, 0
	s_add_i32 s7, s4, 0xfffff000
	v_add_u32_e32 v104, v104, v103
	ds_write_b128 v104, v[64:67]
	ds_write_b128 v104, v[68:71] offset:32
	ds_write_b128 v104, v[72:75] offset:64
	ds_write_b128 v104, v[76:79] offset:96
	ds_write_b128 v104, v[80:83] offset:128
	ds_write_b128 v104, v[84:87] offset:160
	ds_write_b128 v104, v[88:91] offset:192
	ds_write_b128 v104, v[92:95] offset:224
	v_xor_b32_e32 v64, s7, v113
	s_movk_i32 s4, 0x400
	v_lshl_or_b32 v97, v112, 4, v97
	v_cmp_gt_u32_e32 vcc, s4, v64
	v_mad_u32_u24 v115, v128, s5, v97
	s_and_b64 s[4:5], s[2:3], vcc
	v_cndmask_b32_e64 v71, 0, 1, s[4:5]
	s_movk_i32 s4, 0x1000
	v_cmp_gt_i32_e32 vcc, s4, v100
	v_subrev_u32_e32 v114, s8, v98
	v_lshl_add_u32 v103, v114, 2, v167
	v_cndmask_b32_e32 v64, v71, v102, vcc
	v_and_b32_e32 v64, 1, v64
	v_cmp_eq_u32_e32 vcc, 1, v64
	v_ashrrev_i32_e32 v68, 6, v105
	s_mov_b32 s4, 0xc000
	v_cndmask_b32_e64 v64, v171, 0, vcc
	v_add_u32_e32 v70, v103, v64
	ds_read_b128 v[64:67], v115
	ds_read_b128 v[72:75], v70
	v_cmp_eq_u32_e64 s[36:37], 0, v112
	v_mad_i64_i32 v[68:69], s[4:5], v68, s4, 0
	s_and_b64 vcc, exec, s[0:1]
	s_waitcnt lgkmcnt(0)
	v_pk_fma_f32 v[66:67], v[66:67], v[74:75], v[200:201]
	v_pk_fma_f32 v[64:65], v[64:65], v[72:73], v[198:199]
	global_store_dwordx4 v[110:111], v[64:67], off
	s_cbranch_vccnz .LBB0_1439
	ds_read_b128 v[72:75], v70 offset:2048
	v_lshlrev_b64 v[76:77], 10, v[100:101]
	v_lshl_add_u64 v[76:77], v[76:77], 1, s[50:51]
	v_lshl_add_u64 v[76:77], v[98:99], 1, v[76:77]
	s_waitcnt lgkmcnt(0)
	v_pk_mul_f32 v[72:73], v[64:65], v[72:73]
	v_pk_mul_f32 v[64:65], v[64:65], v[64:65]
	v_pk_mul_f32 v[74:75], v[66:67], v[74:75]
	v_pk_mul_f32 v[66:67], v[66:67], v[66:67]
	v_add_f32_e32 v64, v64, v65
	v_add_f32_e32 v64, v66, v64
	v_add_f32_e32 v64, v67, v64
	v_cvt_pk_bf16_f32 v72, v72, v73
	v_cvt_pk_bf16_f32 v73, v74, v75
	v_add_f32_dpp v64, v64, v64 quad_perm:[1,0,3,2] row_mask:0xf bank_mask:0xf bound_ctrl:1
	global_store_dwordx2 v[76:77], v[72:73], off
	s_nop 0
	v_add_f32_dpp v64, v64, v64 quad_perm:[2,3,0,1] row_mask:0xf bank_mask:0xf bound_ctrl:1
	s_nop 1
	v_add_f32_dpp v64, v64, v64 row_half_mirror row_mask:0xf bank_mask:0xf bound_ctrl:1
	s_nop 1
	v_mov_b32_dpp v65, v64 row_mirror row_mask:0xf bank_mask:0xf bound_ctrl:1
	s_and_saveexec_b64 s[4:5], s[36:37]
	s_cbranch_execz .LBB0_1438
	v_lshl_add_u64 v[66:67], s[54:55], 0, v[68:69]
	v_lshl_add_u64 v[66:67], v[100:101], 2, v[66:67]
	v_add_f32_e32 v64, v64, v65
	global_store_dword v[66:67], v64, off
